# proj GEMM: last two K iterations also software-pipelined (hipcc's peeled iterations replaced)
# speedup vs baseline: 1.0077x; 1.0077x over previous
; #define MFMA32(a, b, c) __builtin_amdgcn_mfma_f32_32x32x16_bf16((a), (b), (c), 0, 0, 0)
; #define G_LOAD(KOFF) do { rw0 = *(const uint4*)(gw + (KOFF)); rw1 = *(const uint4*)(gw1 + (KOFF)); rw2 = *(const uint4*)(gw2 + (KOFF)); rw3 = *(const uint4*)(gw3 + (KOFF)); \
;                           rx0 = *(const uint4*)(gx + (KOFF)); rx1 = *(const uint4*)(gx1 + (KOFF)); rx2 = *(const uint4*)(gx2 + (KOFF)); rx3 = *(const uint4*)(gx3 + (KOFF)); } while (0)
; DI void gemm128(const u16* __restrict__ W, int ldw, const u16* __restrict__ X, int ldx, int K, f32x16 (&acc)[2][2], char* smem) {
;     ...
;   for (int kt = 0; kt < nk; ++kt) {
;     const int buf = kt & 1;
; #pragma unroll
;     for (int ks = 0; ks < 4; ++ks) {
;       bf16x8 a0 = *(const bf16x8*)&sw[buf][wn * 64 + r][ks * 16 + h * 8];
;       bf16x8 a1 = *(const bf16x8*)&sw[buf][wn * 64 + 32 + r][ks * 16 + h * 8];
;       bf16x8 b0 = *(const bf16x8*)&sx[buf][wm * 64 + r][ks * 16 + h * 8];
;       bf16x8 b1 = *(const bf16x8*)&sx[buf][wm * 64 + 32 + r][ks * 16 + h * 8];
;       acc[0][0] = MFMA32(a0, b0, acc[0][0]);
;       acc[0][1] = MFMA32(a0, b1, acc[0][1]);
;       acc[1][0] = MFMA32(a1, b0, acc[1][0]);
;       acc[1][1] = MFMA32(a1, b1, acc[1][1]);
;     }
;     if (kt + 1 < nk) G_STORE(buf ^ 1);
;     if (kt + 2 < nk) G_LOAD((kt + 2) * 64);
;     __syncthreads();
;   }
.Lproj_kloop:
	s_and_b32 s12, s11, 1
	s_mul_i32 s13, s12, 0x4800
	s_xor_b32 s12, s12, 1
	s_mulk_i32 s12, 0x4800
	v_add_u32_e32 v121, s13, v101
	v_add_u32_e32 v126, s13, v120
	v_add_u32_e32 v234, s12, v100
	v_add_u32_e32 v235, s12, v101
	v_add_u32_e32 v239, s12, v120
	ds_read_b128 v[158:161], v121 offset:32
	ds_read_b128 v[166:169], v126 offset:36896
	ds_read_b128 v[170:173], v126 offset:41504
	ds_read_b128 v[130:133], v121 offset:4640
	s_waitcnt lgkmcnt(6)
	v_mfma_f32_32x32x16_bf16 v[52:67], v[154:157], v[162:165], v[52:67]
	s_waitcnt vmcnt(8)
	ds_write_b128 v234, v[68:71]
	ds_write_b128 v234, v[72:75] offset:4608
	global_load_dwordx4 v[68:71], v[178:179], off offset:384
	global_load_dwordx4 v[72:75], v[180:181], off offset:384
	s_waitcnt lgkmcnt(7)
	v_mfma_f32_32x32x16_bf16 v[20:35], v[154:157], v[150:153], v[20:35]
	ds_write_b128 v234, v[76:79] offset:9216
	ds_write_b128 v234, v[80:83] offset:13824
	global_load_dwordx4 v[76:79], v[182:183], off offset:384
	global_load_dwordx4 v[80:83], v[184:185], off offset:384
	s_waitcnt lgkmcnt(8)
	v_mfma_f32_32x32x16_bf16 v[36:51], v[122:125], v[162:165], v[36:51]
	ds_write_b128 v234, v[84:87] offset:36864
	ds_write_b128 v234, v[88:91] offset:41472
	global_load_dwordx4 v[84:87], v[186:187], off offset:384
	global_load_dwordx4 v[88:91], v[188:189], off offset:384
	v_mfma_f32_32x32x16_bf16 v[4:19], v[122:125], v[150:153], v[4:19]
	ds_write_b128 v234, v[92:95] offset:46080
	ds_write_b128 v234, v[96:99] offset:50688
	global_load_dwordx4 v[92:95], v[190:191], off offset:384
	global_load_dwordx4 v[96:99], v[192:193], off offset:384
	ds_read_b128 v[154:157], v121 offset:64
	ds_read_b128 v[162:165], v126 offset:36928
	ds_read_b128 v[150:153], v126 offset:41536
	ds_read_b128 v[122:125], v121 offset:4672
	s_waitcnt lgkmcnt(14)
	v_mfma_f32_32x32x16_bf16 v[52:67], v[158:161], v[166:169], v[52:67]
	s_waitcnt lgkmcnt(13)
	v_mfma_f32_32x32x16_bf16 v[20:35], v[158:161], v[170:173], v[20:35]
	s_waitcnt lgkmcnt(12)
	v_mfma_f32_32x32x16_bf16 v[36:51], v[130:133], v[166:169], v[36:51]
	v_mfma_f32_32x32x16_bf16 v[4:19], v[130:133], v[170:173], v[4:19]
	ds_read_b128 v[158:161], v121 offset:96
	ds_read_b128 v[166:169], v126 offset:36960
	ds_read_b128 v[170:173], v126 offset:41568
	ds_read_b128 v[130:133], v121 offset:4704
	s_waitcnt lgkmcnt(6)
	v_mfma_f32_32x32x16_bf16 v[52:67], v[154:157], v[162:165], v[52:67]
	v_lshl_add_u64 v[178:179], v[178:179], 0, s[6:7]
	v_lshl_add_u64 v[180:181], v[180:181], 0, s[6:7]
	v_lshl_add_u64 v[182:183], v[182:183], 0, s[6:7]
	s_waitcnt lgkmcnt(5)
	v_mfma_f32_32x32x16_bf16 v[20:35], v[154:157], v[150:153], v[20:35]
	v_lshl_add_u64 v[184:185], v[184:185], 0, s[6:7]
	v_lshl_add_u64 v[186:187], v[186:187], 0, s[6:7]
	v_lshl_add_u64 v[188:189], v[188:189], 0, s[6:7]
	s_waitcnt lgkmcnt(4)
	v_mfma_f32_32x32x16_bf16 v[36:51], v[122:125], v[162:165], v[36:51]
	v_lshl_add_u64 v[190:191], v[190:191], 0, s[6:7]
	v_lshl_add_u64 v[192:193], v[192:193], 0, s[6:7]
	v_mfma_f32_32x32x16_bf16 v[4:19], v[122:125], v[150:153], v[4:19]
	s_add_i32 s11, s11, 1
	s_waitcnt lgkmcnt(0)
	s_barrier
	ds_read_b128 v[154:157], v235
	ds_read_b128 v[162:165], v239 offset:36864
	ds_read_b128 v[150:153], v239 offset:41472
	ds_read_b128 v[122:125], v235 offset:4608
	v_mfma_f32_32x32x16_bf16 v[52:67], v[158:161], v[166:169], v[52:67]
	v_mfma_f32_32x32x16_bf16 v[20:35], v[158:161], v[170:173], v[20:35]
	v_mfma_f32_32x32x16_bf16 v[36:51], v[130:133], v[166:169], v[36:51]
	v_mfma_f32_32x32x16_bf16 v[4:19], v[130:133], v[170:173], v[4:19]
	s_and_b32 s12, s11, 1
	s_mul_i32 s13, s12, 0x4800
	s_xor_b32 s12, s12, 1
	s_mulk_i32 s12, 0x4800
	v_add_u32_e32 v121, s13, v101
	v_add_u32_e32 v126, s13, v120
	v_add_u32_e32 v234, s12, v100
	v_add_u32_e32 v235, s12, v101
	v_add_u32_e32 v239, s12, v120
	ds_read_b128 v[158:161], v121 offset:32
	ds_read_b128 v[166:169], v126 offset:36896
	ds_read_b128 v[170:173], v126 offset:41504
	ds_read_b128 v[130:133], v121 offset:4640
	s_waitcnt lgkmcnt(6)
	v_mfma_f32_32x32x16_bf16 v[52:67], v[154:157], v[162:165], v[52:67]
	s_waitcnt vmcnt(8)
	ds_write_b128 v234, v[174:177]
	ds_write_b128 v234, v[194:197] offset:4608
	global_load_dwordx4 v[174:177], v[178:179], off offset:384
	global_load_dwordx4 v[194:197], v[180:181], off offset:384
	s_waitcnt lgkmcnt(7)
	v_mfma_f32_32x32x16_bf16 v[20:35], v[154:157], v[150:153], v[20:35]
	ds_write_b128 v234, v[198:201] offset:9216
	ds_write_b128 v234, v[230:233] offset:13824
	global_load_dwordx4 v[198:201], v[182:183], off offset:384
	global_load_dwordx4 v[230:233], v[184:185], off offset:384
	s_waitcnt lgkmcnt(8)
	v_mfma_f32_32x32x16_bf16 v[36:51], v[122:125], v[162:165], v[36:51]
	ds_write_b128 v234, v[240:243] offset:36864
	ds_write_b128 v234, v[244:247] offset:41472
	global_load_dwordx4 v[240:243], v[186:187], off offset:384
	global_load_dwordx4 v[244:247], v[188:189], off offset:384
	v_mfma_f32_32x32x16_bf16 v[4:19], v[122:125], v[150:153], v[4:19]
	ds_write_b128 v234, v[248:251] offset:46080
	ds_write_b128 v234, v[102:105] offset:50688
	global_load_dwordx4 v[248:251], v[190:191], off offset:384
	global_load_dwordx4 v[102:105], v[192:193], off offset:384
	ds_read_b128 v[154:157], v121 offset:64
	ds_read_b128 v[162:165], v126 offset:36928
	ds_read_b128 v[150:153], v126 offset:41536
	ds_read_b128 v[122:125], v121 offset:4672
	s_waitcnt lgkmcnt(14)
	v_mfma_f32_32x32x16_bf16 v[52:67], v[158:161], v[166:169], v[52:67]
	s_waitcnt lgkmcnt(13)
	v_mfma_f32_32x32x16_bf16 v[20:35], v[158:161], v[170:173], v[20:35]
	s_waitcnt lgkmcnt(12)
	v_mfma_f32_32x32x16_bf16 v[36:51], v[130:133], v[166:169], v[36:51]
	v_mfma_f32_32x32x16_bf16 v[4:19], v[130:133], v[170:173], v[4:19]
	ds_read_b128 v[158:161], v121 offset:96
	ds_read_b128 v[166:169], v126 offset:36960
	ds_read_b128 v[170:173], v126 offset:41568
	ds_read_b128 v[130:133], v121 offset:4704
	s_waitcnt lgkmcnt(6)
	v_mfma_f32_32x32x16_bf16 v[52:67], v[154:157], v[162:165], v[52:67]
	v_lshl_add_u64 v[178:179], v[178:179], 0, s[6:7]
	v_lshl_add_u64 v[180:181], v[180:181], 0, s[6:7]
	v_lshl_add_u64 v[182:183], v[182:183], 0, s[6:7]
	s_waitcnt lgkmcnt(5)
	v_mfma_f32_32x32x16_bf16 v[20:35], v[154:157], v[150:153], v[20:35]
	v_lshl_add_u64 v[184:185], v[184:185], 0, s[6:7]
	v_lshl_add_u64 v[186:187], v[186:187], 0, s[6:7]
	v_lshl_add_u64 v[188:189], v[188:189], 0, s[6:7]
	s_waitcnt lgkmcnt(4)
	v_mfma_f32_32x32x16_bf16 v[36:51], v[122:125], v[162:165], v[36:51]
	v_lshl_add_u64 v[190:191], v[190:191], 0, s[6:7]
	v_lshl_add_u64 v[192:193], v[192:193], 0, s[6:7]
	v_mfma_f32_32x32x16_bf16 v[4:19], v[122:125], v[150:153], v[4:19]
	s_add_i32 s11, s11, 1
	s_waitcnt lgkmcnt(0)
	s_barrier
; #define MFMA32(a, b, c) __builtin_amdgcn_mfma_f32_32x32x16_bf16((a), (b), (c), 0, 0, 0)
; #define G_LOAD(KOFF) do { rw0 = *(const uint4*)(gw + (KOFF)); rw1 = *(const uint4*)(gw1 + (KOFF)); rw2 = *(const uint4*)(gw2 + (KOFF)); rw3 = *(const uint4*)(gw3 + (KOFF)); \
;                           rx0 = *(const uint4*)(gx + (KOFF)); rx1 = *(const uint4*)(gx1 + (KOFF)); rx2 = *(const uint4*)(gx2 + (KOFF)); rx3 = *(const uint4*)(gx3 + (KOFF)); } while (0)
; DI void gemm128(const u16* __restrict__ W, int ldw, const u16* __restrict__ X, int ldx, int K, f32x16 (&acc)[2][2], char* smem) {
;     ...
;   for (int kt = 0; kt < nk; ++kt) {
;     const int buf = kt & 1;
; #pragma unroll
;     for (int ks = 0; ks < 4; ++ks) {
;       bf16x8 a0 = *(const bf16x8*)&sw[buf][wn * 64 + r][ks * 16 + h * 8];
;       bf16x8 a1 = *(const bf16x8*)&sw[buf][wn * 64 + 32 + r][ks * 16 + h * 8];
;       bf16x8 b0 = *(const bf16x8*)&sx[buf][wm * 64 + r][ks * 16 + h * 8];
;       bf16x8 b1 = *(const bf16x8*)&sx[buf][wm * 64 + 32 + r][ks * 16 + h * 8];
;       acc[0][0] = MFMA32(a0, b0, acc[0][0]);
;       acc[0][1] = MFMA32(a0, b1, acc[0][1]);
;       acc[1][0] = MFMA32(a1, b0, acc[1][0]);
;       acc[1][1] = MFMA32(a1, b1, acc[1][1]);
;     }
;     if (kt + 1 < nk) G_STORE(buf ^ 1);
;     if (kt + 2 < nk) G_LOAD((kt + 2) * 64);
;     __syncthreads();
;   }
	ds_read_b128 v[154:157], v235
	ds_read_b128 v[162:165], v239 offset:36864
	ds_read_b128 v[150:153], v239 offset:41472
	ds_read_b128 v[122:125], v235 offset:4608
	v_mfma_f32_32x32x16_bf16 v[52:67], v[158:161], v[166:169], v[52:67]
	v_mfma_f32_32x32x16_bf16 v[20:35], v[158:161], v[170:173], v[20:35]
	v_mfma_f32_32x32x16_bf16 v[36:51], v[130:133], v[166:169], v[36:51]
	v_mfma_f32_32x32x16_bf16 v[4:19], v[130:133], v[170:173], v[4:19]
	s_cmp_lt_u32 s11, 12
	s_cbranch_scc1 .Lproj_kloop
	s_and_b32 s12, s11, 1
	s_mul_i32 s13, s12, 0x4800
	s_xor_b32 s12, s12, 1
	s_mulk_i32 s12, 0x4800
	v_add_u32_e32 v121, s13, v101
	v_add_u32_e32 v126, s13, v120
	v_add_u32_e32 v234, s12, v100
	v_add_u32_e32 v235, s12, v101
	v_add_u32_e32 v239, s12, v120
	ds_read_b128 v[158:161], v121 offset:32
	ds_read_b128 v[166:169], v126 offset:36896
	ds_read_b128 v[170:173], v126 offset:41504
	ds_read_b128 v[130:133], v121 offset:4640
	s_waitcnt lgkmcnt(6)
	v_mfma_f32_32x32x16_bf16 v[52:67], v[154:157], v[162:165], v[52:67]
	s_waitcnt vmcnt(8)
	ds_write_b128 v234, v[68:71]
	ds_write_b128 v234, v[72:75] offset:4608
	global_load_dwordx4 v[68:71], v[178:179], off offset:384
	global_load_dwordx4 v[72:75], v[180:181], off offset:384
	s_waitcnt lgkmcnt(7)
	v_mfma_f32_32x32x16_bf16 v[20:35], v[154:157], v[150:153], v[20:35]
	ds_write_b128 v234, v[76:79] offset:9216
	ds_write_b128 v234, v[80:83] offset:13824
	global_load_dwordx4 v[76:79], v[182:183], off offset:384
	global_load_dwordx4 v[80:83], v[184:185], off offset:384
	s_waitcnt lgkmcnt(8)
	v_mfma_f32_32x32x16_bf16 v[36:51], v[122:125], v[162:165], v[36:51]
	ds_write_b128 v234, v[84:87] offset:36864
	ds_write_b128 v234, v[88:91] offset:41472
	global_load_dwordx4 v[84:87], v[186:187], off offset:384
	global_load_dwordx4 v[88:91], v[188:189], off offset:384
	v_mfma_f32_32x32x16_bf16 v[4:19], v[122:125], v[150:153], v[4:19]
	ds_write_b128 v234, v[92:95] offset:46080
	ds_write_b128 v234, v[96:99] offset:50688
	global_load_dwordx4 v[92:95], v[190:191], off offset:384
	global_load_dwordx4 v[96:99], v[192:193], off offset:384
	ds_read_b128 v[154:157], v121 offset:64
	ds_read_b128 v[162:165], v126 offset:36928
	ds_read_b128 v[150:153], v126 offset:41536
	ds_read_b128 v[122:125], v121 offset:4672
	s_waitcnt lgkmcnt(14)
	v_mfma_f32_32x32x16_bf16 v[52:67], v[158:161], v[166:169], v[52:67]
	s_waitcnt lgkmcnt(13)
	v_mfma_f32_32x32x16_bf16 v[20:35], v[158:161], v[170:173], v[20:35]
	s_waitcnt lgkmcnt(12)
	v_mfma_f32_32x32x16_bf16 v[36:51], v[130:133], v[166:169], v[36:51]
	v_mfma_f32_32x32x16_bf16 v[4:19], v[130:133], v[170:173], v[4:19]
	ds_read_b128 v[158:161], v121 offset:96
	ds_read_b128 v[166:169], v126 offset:36960
	ds_read_b128 v[170:173], v126 offset:41568
	ds_read_b128 v[130:133], v121 offset:4704
	s_waitcnt lgkmcnt(6)
	v_mfma_f32_32x32x16_bf16 v[52:67], v[154:157], v[162:165], v[52:67]
	v_lshl_add_u64 v[178:179], v[178:179], 0, s[6:7]
	v_lshl_add_u64 v[180:181], v[180:181], 0, s[6:7]
	v_lshl_add_u64 v[182:183], v[182:183], 0, s[6:7]
	s_waitcnt lgkmcnt(5)
	v_mfma_f32_32x32x16_bf16 v[20:35], v[154:157], v[150:153], v[20:35]
	v_lshl_add_u64 v[184:185], v[184:185], 0, s[6:7]
	v_lshl_add_u64 v[186:187], v[186:187], 0, s[6:7]
	v_lshl_add_u64 v[188:189], v[188:189], 0, s[6:7]
	s_waitcnt lgkmcnt(4)
	v_mfma_f32_32x32x16_bf16 v[36:51], v[122:125], v[162:165], v[36:51]
	v_lshl_add_u64 v[190:191], v[190:191], 0, s[6:7]
	v_lshl_add_u64 v[192:193], v[192:193], 0, s[6:7]
	v_mfma_f32_32x32x16_bf16 v[4:19], v[122:125], v[150:153], v[4:19]
	s_add_i32 s11, s11, 1
	s_waitcnt lgkmcnt(0)
	s_barrier
	ds_read_b128 v[154:157], v235
	ds_read_b128 v[162:165], v239 offset:36864
	ds_read_b128 v[150:153], v239 offset:41472
	ds_read_b128 v[122:125], v235 offset:4608
	v_mfma_f32_32x32x16_bf16 v[52:67], v[158:161], v[166:169], v[52:67]
	v_mfma_f32_32x32x16_bf16 v[20:35], v[158:161], v[170:173], v[20:35]
	v_mfma_f32_32x32x16_bf16 v[36:51], v[130:133], v[166:169], v[36:51]
	v_mfma_f32_32x32x16_bf16 v[4:19], v[130:133], v[170:173], v[4:19]
	s_and_b32 s12, s11, 1
	s_mul_i32 s13, s12, 0x4800
	s_xor_b32 s12, s12, 1
	s_mulk_i32 s12, 0x4800
	v_add_u32_e32 v121, s13, v101
	v_add_u32_e32 v126, s13, v120
	v_add_u32_e32 v234, s12, v100
	v_add_u32_e32 v235, s12, v101
	v_add_u32_e32 v239, s12, v120
	ds_read_b128 v[158:161], v121 offset:32
	ds_read_b128 v[166:169], v126 offset:36896
	ds_read_b128 v[170:173], v126 offset:41504
	ds_read_b128 v[130:133], v121 offset:4640
	s_waitcnt lgkmcnt(6)
	v_mfma_f32_32x32x16_bf16 v[52:67], v[154:157], v[162:165], v[52:67]
	s_waitcnt vmcnt(8)
	ds_write_b128 v234, v[174:177]
	ds_write_b128 v234, v[194:197] offset:4608
	s_waitcnt lgkmcnt(7)
	v_mfma_f32_32x32x16_bf16 v[20:35], v[154:157], v[150:153], v[20:35]
	ds_write_b128 v234, v[198:201] offset:9216
	ds_write_b128 v234, v[230:233] offset:13824
	s_waitcnt lgkmcnt(8)
	v_mfma_f32_32x32x16_bf16 v[36:51], v[122:125], v[162:165], v[36:51]
	ds_write_b128 v234, v[240:243] offset:36864
	ds_write_b128 v234, v[244:247] offset:41472
	v_mfma_f32_32x32x16_bf16 v[4:19], v[122:125], v[150:153], v[4:19]
	ds_write_b128 v234, v[248:251] offset:46080
	ds_write_b128 v234, v[102:105] offset:50688
	ds_read_b128 v[154:157], v121 offset:64
	ds_read_b128 v[162:165], v126 offset:36928
	ds_read_b128 v[150:153], v126 offset:41536
	ds_read_b128 v[122:125], v121 offset:4672
	s_waitcnt lgkmcnt(14)
	v_mfma_f32_32x32x16_bf16 v[52:67], v[158:161], v[166:169], v[52:67]
	s_waitcnt lgkmcnt(13)
	v_mfma_f32_32x32x16_bf16 v[20:35], v[158:161], v[170:173], v[20:35]
	s_waitcnt lgkmcnt(12)
	v_mfma_f32_32x32x16_bf16 v[36:51], v[130:133], v[166:169], v[36:51]
	v_mfma_f32_32x32x16_bf16 v[4:19], v[130:133], v[170:173], v[4:19]
	ds_read_b128 v[158:161], v121 offset:96
	ds_read_b128 v[166:169], v126 offset:36960
	ds_read_b128 v[170:173], v126 offset:41568
	ds_read_b128 v[130:133], v121 offset:4704
	s_waitcnt lgkmcnt(6)
	v_mfma_f32_32x32x16_bf16 v[52:67], v[154:157], v[162:165], v[52:67]
	v_lshl_add_u64 v[178:179], v[178:179], 0, s[6:7]
	v_lshl_add_u64 v[180:181], v[180:181], 0, s[6:7]
	v_lshl_add_u64 v[182:183], v[182:183], 0, s[6:7]
	s_waitcnt lgkmcnt(5)
	v_mfma_f32_32x32x16_bf16 v[20:35], v[154:157], v[150:153], v[20:35]
	v_lshl_add_u64 v[184:185], v[184:185], 0, s[6:7]
	v_lshl_add_u64 v[186:187], v[186:187], 0, s[6:7]
	v_lshl_add_u64 v[188:189], v[188:189], 0, s[6:7]
	s_waitcnt lgkmcnt(4)
	v_mfma_f32_32x32x16_bf16 v[36:51], v[122:125], v[162:165], v[36:51]
	v_lshl_add_u64 v[190:191], v[190:191], 0, s[6:7]
	v_lshl_add_u64 v[192:193], v[192:193], 0, s[6:7]
	v_mfma_f32_32x32x16_bf16 v[4:19], v[122:125], v[150:153], v[4:19]
	s_add_i32 s11, s11, 1
	s_waitcnt lgkmcnt(0)
	s_barrier
; #define MFMA32(a, b, c) __builtin_amdgcn_mfma_f32_32x32x16_bf16((a), (b), (c), 0, 0, 0)
; #define G_LOAD(KOFF) do { rw0 = *(const uint4*)(gw + (KOFF)); rw1 = *(const uint4*)(gw1 + (KOFF)); rw2 = *(const uint4*)(gw2 + (KOFF)); rw3 = *(const uint4*)(gw3 + (KOFF)); \
;                           rx0 = *(const uint4*)(gx + (KOFF)); rx1 = *(const uint4*)(gx1 + (KOFF)); rx2 = *(const uint4*)(gx2 + (KOFF)); rx3 = *(const uint4*)(gx3 + (KOFF)); } while (0)
; DI void gemm128(const u16* __restrict__ W, int ldw, const u16* __restrict__ X, int ldx, int K, f32x16 (&acc)[2][2], char* smem) {
;     ...
;   for (int kt = 0; kt < nk; ++kt) {
;     const int buf = kt & 1;
; #pragma unroll
;     for (int ks = 0; ks < 4; ++ks) {
;       bf16x8 a0 = *(const bf16x8*)&sw[buf][wn * 64 + r][ks * 16 + h * 8];
;       bf16x8 a1 = *(const bf16x8*)&sw[buf][wn * 64 + 32 + r][ks * 16 + h * 8];
;       bf16x8 b0 = *(const bf16x8*)&sx[buf][wm * 64 + r][ks * 16 + h * 8];
;       bf16x8 b1 = *(const bf16x8*)&sx[buf][wm * 64 + 32 + r][ks * 16 + h * 8];
;       acc[0][0] = MFMA32(a0, b0, acc[0][0]);
;       acc[0][1] = MFMA32(a0, b1, acc[0][1]);
;       acc[1][0] = MFMA32(a1, b0, acc[1][0]);
;       acc[1][1] = MFMA32(a1, b1, acc[1][1]);
;     }
;     if (kt + 1 < nk) G_STORE(buf ^ 1);
;     if (kt + 2 < nk) G_LOAD((kt + 2) * 64);
;     __syncthreads();
;   }
; DI void phase_proj(const Params& p, int layer, char* smem, int xcd, int loc, int nloc) {
;     ...
;       const int mb = m0 + wm * 64;
;       const int b = mb >> 12, s0 = mb & 4095;
;       u16 (*st)[72] = (u16 (*)[72])(smem + ((wave & 2) ? 55296 : 18432) + (wave & 1) * 9216);
;       const bool transposed = (nb >= 1024 && nb < 1536) || (nb == N_DSV);
;       const float cs = (nb < 512) ? C_SB : 1.f;
;       u16* dst; size_t rstride;
;       if (nb < 512) { dst = (u16*)(p.ws + WS_QA) + ((size_t)(b * 8 + (nb >> 6)) * 4096 + s0) * 64; rstride = 64; }
;       else if (nb < 1024) { dst = (u16*)(p.ws + WS_KA) + ((size_t)(b * 8 + ((nb - 512) >> 6)) * 4096 + s0) * 64; rstride = 64; }
;       else if (nb < 1536) { dst = VTA + ((size_t)(b * 8 + ((nb - 1024) >> 6)) * 64) * 4096 + s0; rstride = 4096; }
;       else if (nb == N_DSV) { dst = VTC + ((size_t)b * 64) * 4096 + s0; rstride = 4096; }
;       else { dst = PROJ + (size_t)mb * LDP + (nb - 1536); rstride = LDP; }
	ds_read_b128 v[154:157], v235
	ds_read_b128 v[162:165], v239 offset:36864
	ds_read_b128 v[150:153], v239 offset:41472
	ds_read_b128 v[122:125], v235 offset:4608
	v_mfma_f32_32x32x16_bf16 v[52:67], v[158:161], v[166:169], v[52:67]
	v_mfma_f32_32x32x16_bf16 v[20:35], v[158:161], v[170:173], v[20:35]
	v_mfma_f32_32x32x16_bf16 v[36:51], v[130:133], v[166:169], v[36:51]
	v_mfma_f32_32x32x16_bf16 v[4:19], v[130:133], v[170:173], v[4:19]
	s_and_b32 s12, s11, 1
	s_mul_i32 s13, s12, 0x4800
	s_xor_b32 s12, s12, 1
	s_mulk_i32 s12, 0x4800
	v_add_u32_e32 v121, s13, v101
	v_add_u32_e32 v126, s13, v120
	v_add_u32_e32 v234, s12, v100
	v_add_u32_e32 v235, s12, v101
	v_add_u32_e32 v239, s12, v120
	ds_read_b128 v[158:161], v121 offset:32
	ds_read_b128 v[166:169], v126 offset:36896
	ds_read_b128 v[170:173], v126 offset:41504
	ds_read_b128 v[130:133], v121 offset:4640
	s_waitcnt lgkmcnt(6)
	v_mfma_f32_32x32x16_bf16 v[52:67], v[154:157], v[162:165], v[52:67]
	s_waitcnt vmcnt(0)
	ds_write_b128 v234, v[68:71]
	ds_write_b128 v234, v[72:75] offset:4608
	s_waitcnt lgkmcnt(7)
	v_mfma_f32_32x32x16_bf16 v[20:35], v[154:157], v[150:153], v[20:35]
	ds_write_b128 v234, v[76:79] offset:9216
	ds_write_b128 v234, v[80:83] offset:13824
	s_waitcnt lgkmcnt(8)
	v_mfma_f32_32x32x16_bf16 v[36:51], v[122:125], v[162:165], v[36:51]
	ds_write_b128 v234, v[84:87] offset:36864
	ds_write_b128 v234, v[88:91] offset:41472
	v_mfma_f32_32x32x16_bf16 v[4:19], v[122:125], v[150:153], v[4:19]
	ds_write_b128 v234, v[92:95] offset:46080
	ds_write_b128 v234, v[96:99] offset:50688
	ds_read_b128 v[154:157], v121 offset:64
	ds_read_b128 v[162:165], v126 offset:36928
	ds_read_b128 v[150:153], v126 offset:41536
	ds_read_b128 v[122:125], v121 offset:4672
	s_waitcnt lgkmcnt(14)
	v_mfma_f32_32x32x16_bf16 v[52:67], v[158:161], v[166:169], v[52:67]
	s_waitcnt lgkmcnt(13)
	v_mfma_f32_32x32x16_bf16 v[20:35], v[158:161], v[170:173], v[20:35]
	s_waitcnt lgkmcnt(12)
	v_mfma_f32_32x32x16_bf16 v[36:51], v[130:133], v[166:169], v[36:51]
	v_mfma_f32_32x32x16_bf16 v[4:19], v[130:133], v[170:173], v[4:19]
	ds_read_b128 v[158:161], v121 offset:96
	ds_read_b128 v[166:169], v126 offset:36960
	ds_read_b128 v[170:173], v126 offset:41568
	ds_read_b128 v[130:133], v121 offset:4704
	s_waitcnt lgkmcnt(6)
	v_mfma_f32_32x32x16_bf16 v[52:67], v[154:157], v[162:165], v[52:67]
	s_waitcnt lgkmcnt(5)
	v_mfma_f32_32x32x16_bf16 v[20:35], v[154:157], v[150:153], v[20:35]
	s_waitcnt lgkmcnt(4)
	v_mfma_f32_32x32x16_bf16 v[36:51], v[122:125], v[162:165], v[36:51]
	v_mfma_f32_32x32x16_bf16 v[4:19], v[122:125], v[150:153], v[4:19]
	s_add_i32 s11, s11, 1
	s_waitcnt lgkmcnt(0)
	s_barrier
	ds_read_b128 v[154:157], v235
	ds_read_b128 v[162:165], v239 offset:36864
	ds_read_b128 v[150:153], v239 offset:41472
	ds_read_b128 v[122:125], v235 offset:4608
	v_mfma_f32_32x32x16_bf16 v[52:67], v[158:161], v[166:169], v[52:67]
	v_mfma_f32_32x32x16_bf16 v[20:35], v[158:161], v[170:173], v[20:35]
	v_mfma_f32_32x32x16_bf16 v[36:51], v[130:133], v[166:169], v[36:51]
	v_mfma_f32_32x32x16_bf16 v[4:19], v[130:133], v[170:173], v[4:19]
	s_and_b32 s12, s11, 1
	s_mul_i32 s13, s12, 0x4800
	s_xor_b32 s12, s12, 1
	s_mulk_i32 s12, 0x4800
	v_add_u32_e32 v121, s13, v101
	v_add_u32_e32 v126, s13, v120
	v_add_u32_e32 v234, s12, v100
	v_add_u32_e32 v235, s12, v101
	v_add_u32_e32 v239, s12, v120
	ds_read_b128 v[158:161], v121 offset:32
	ds_read_b128 v[166:169], v126 offset:36896
	ds_read_b128 v[170:173], v126 offset:41504
	ds_read_b128 v[130:133], v121 offset:4640
	s_waitcnt lgkmcnt(6)
	v_mfma_f32_32x32x16_bf16 v[52:67], v[154:157], v[162:165], v[52:67]
	s_waitcnt lgkmcnt(5)
	v_mfma_f32_32x32x16_bf16 v[20:35], v[154:157], v[150:153], v[20:35]
	s_waitcnt lgkmcnt(4)
	v_mfma_f32_32x32x16_bf16 v[36:51], v[122:125], v[162:165], v[36:51]
	v_mfma_f32_32x32x16_bf16 v[4:19], v[122:125], v[150:153], v[4:19]
	ds_read_b128 v[154:157], v121 offset:64
	ds_read_b128 v[162:165], v126 offset:36928
	ds_read_b128 v[150:153], v126 offset:41536
	ds_read_b128 v[122:125], v121 offset:4672
	s_waitcnt lgkmcnt(6)
	v_mfma_f32_32x32x16_bf16 v[52:67], v[158:161], v[166:169], v[52:67]
	s_waitcnt lgkmcnt(5)
	v_mfma_f32_32x32x16_bf16 v[20:35], v[158:161], v[170:173], v[20:35]
	s_waitcnt lgkmcnt(4)
	v_mfma_f32_32x32x16_bf16 v[36:51], v[130:133], v[166:169], v[36:51]
	v_mfma_f32_32x32x16_bf16 v[4:19], v[130:133], v[170:173], v[4:19]
	ds_read_b128 v[158:161], v121 offset:96
	ds_read_b128 v[166:169], v126 offset:36960
	ds_read_b128 v[170:173], v126 offset:41568
	ds_read_b128 v[130:133], v121 offset:4704
	s_waitcnt lgkmcnt(6)
	v_mfma_f32_32x32x16_bf16 v[52:67], v[154:157], v[162:165], v[52:67]
	s_waitcnt lgkmcnt(5)
	v_mfma_f32_32x32x16_bf16 v[20:35], v[154:157], v[150:153], v[20:35]
	s_waitcnt lgkmcnt(4)
	v_mfma_f32_32x32x16_bf16 v[36:51], v[122:125], v[162:165], v[36:51]
	v_mfma_f32_32x32x16_bf16 v[4:19], v[122:125], v[150:153], v[4:19]
	s_add_i32 s11, s11, 1
	s_waitcnt lgkmcnt(0)
	s_barrier
	v_mfma_f32_32x32x16_bf16 v[52:67], v[158:161], v[166:169], v[52:67]
	v_mfma_f32_32x32x16_bf16 v[20:35], v[158:161], v[170:173], v[20:35]
	v_mfma_f32_32x32x16_bf16 v[36:51], v[130:133], v[166:169], v[36:51]
	v_mfma_f32_32x32x16_bf16 v[4:19], v[130:133], v[170:173], v[4:19]
	s_add_i32 s51, s10, s36
	s_or_b32 s16, s15, s37
	s_ashr_i32 s14, s51, 12
	s_and_b32 s52, s51, 0xfc0
	s_cmpk_eq_i32 s16, 0x9c0
	s_cselect_b64 s[12:13], -1, 0
	s_cmpk_lg_i32 s16, 0x9c0
	s_cselect_b64 s[18:19], -1, 0
	s_cmpk_lt_i32 s16, 0x200
	s_cselect_b64 s[48:49], -1, 0
	s_cmpk_gt_i32 s16, 0x1ff
	s_mov_b64 s[28:29], -1
	s_cbranch_scc0 .LBB0_1430
	s_cmpk_gt_u32 s15, 0x3ff
	s_cbranch_scc0 .LBB0_1427
	s_cmpk_gt_i32 s16, 0x5ff
	s_cbranch_scc0 .LBB0_1424
	s_mov_b64 s[6:7], -1
	s_and_b64 vcc, exec, s[18:19]
	s_cbranch_vccz .LBB0_1421
	s_mul_i32 s7, s51, 0x2f00
	s_mul_hi_i32 s6, s51, 0x2f00
	s_add_u32 s10, s94, s7
	s_addc_u32 s11, s95, s6
	s_lshl_b64 s[6:7], s[16:17], 1
	s_add_u32 s6, s10, s6
	s_addc_u32 s7, s11, s7
	s_add_u32 s10, s6, 0x4e97400
	s_addc_u32 s11, s7, 0
	s_mov_b64 s[6:7], 0
